# mixer schedule rebalanced (sample jobs on workgroups with fewer prompt jobs), sample pool W=4/W=2 windows hand-scheduled, layer-loop grid barriers one hop shorter
# speedup vs baseline: 1.0462x; 1.0052x over previous
.LBB0_145:
	v_writelane_b32 v252, s56, 34
	s_nop 1
	v_writelane_b32 v252, s57, 35
	s_or_b64 exec, exec, s[0:1]
	s_add_u32 s80, s10, 0xec00000
	s_addc_u32 s81, s11, 0
	s_add_u32 s25, s10, 0x3800000
	s_addc_u32 s26, s11, 0
	s_add_u32 s0, s10, 0x5a00000
	s_addc_u32 s1, s11, 0
	s_add_u32 s4, s10, 0x400000
	v_writelane_b32 v252, s4, 36
	s_addc_u32 s4, s11, 0
	s_cmpk_lt_i32 s2, 0x400
	v_writelane_b32 v252, s4, 37
	s_cselect_b64 s[4:5], -1, 0
	v_writelane_b32 v252, s4, 38
	s_ashr_i32 s33, s2, 31
	s_ashr_i32 s13, s96, 31
	v_writelane_b32 v252, s5, 39
	s_lshr_b32 s4, s33, 29
	s_add_i32 s5, s2, s4
	s_ashr_i32 s4, s5, 3
	s_and_b32 s5, s5, -8
	s_sub_i32 s6, s2, s5
	s_lshl_b32 s7, s6, 7
	s_and_b32 s5, s1, 0xffff
	s_add_u32 s14, s10, 0xf000200
	s_addc_u32 s15, s11, 0
	s_add_u32 s62, s10, 0xf000400
	s_addc_u32 s63, s11, 0
	s_add_u32 s28, s10, 0xf000500
	v_writelane_b32 v252, s14, 40
	s_addc_u32 s29, s11, 0
	v_lshl_add_u64 v[0:1], v[0:1], 2, s[52:53]
	v_writelane_b32 v252, s15, 41
	s_add_u32 s14, s10, 0xf000600
	s_addc_u32 s15, s11, 0
	v_writelane_b32 v252, s14, 42
	s_mov_b32 s69, 0
	s_mul_i32 s97, s97, s96
	v_writelane_b32 v252, s15, 43
	s_add_u32 s14, s10, 0xf000700
	s_addc_u32 s15, s11, 0
	v_writelane_b32 v252, s14, 44
	s_mul_i32 s97, s97, s54
	s_mov_b32 s83, 0x20000
	v_writelane_b32 v252, s15, 45
	s_add_u32 s14, s10, 0xf000800
	s_addc_u32 s15, s11, 0
	v_writelane_b32 v252, s14, 46
	s_mov_b32 s82, 0x7ffffff0
	v_mov_b32_e32 v161, 0
	v_writelane_b32 v252, s15, 47
	s_add_u32 s14, s10, 0xf000900
	s_addc_u32 s15, s11, 0
	v_writelane_b32 v252, s14, 48
	v_mov_b32_e32 v228, 1
	v_mov_b32_e32 v229, 0x358637bd
	v_writelane_b32 v252, s15, 49
	s_add_u32 s14, s10, 0xf000a00
	s_addc_u32 s15, s11, 0
	v_writelane_b32 v252, s14, 50
	v_mov_b32_e32 v230, 0xec00000
	v_mov_b32_e32 v231, 0xc0
	v_writelane_b32 v252, s15, 51
	s_add_u32 s14, s10, 0xf000b00
	s_addc_u32 s15, s11, 0
	v_writelane_b32 v252, s14, 52
	s_mov_b64 s[76:77], 0x80
	s_nop 0
	v_writelane_b32 v252, s15, 53
	s_add_u32 s14, s10, 0xf000c00
	s_addc_u32 s15, s11, 0
	v_writelane_b32 v252, s14, 54
	s_barrier
	s_nop 0
	v_writelane_b32 v252, s15, 55
	s_add_u32 s14, s10, 0xf000d00
	s_addc_u32 s15, s11, 0
	v_writelane_b32 v252, s14, 56
	s_nop 1
	v_writelane_b32 v252, s15, 57
	s_add_u32 s14, s10, 0xf000e00
	s_addc_u32 s15, s11, 0
	v_writelane_b32 v252, s14, 58
	s_nop 1
	v_writelane_b32 v252, s15, 59
	s_add_u32 s14, s10, 0xf000f00
	s_addc_u32 s15, s11, 0
	v_writelane_b32 v252, s14, 60
	s_nop 1
	v_writelane_b32 v252, s15, 61
	s_add_u32 s14, s10, 0xf001000
	s_addc_u32 s15, s11, 0
	s_add_u32 s86, s10, 0xf001100
	s_addc_u32 s87, s11, 0
	s_add_u32 s74, s10, 0xf001200
	s_addc_u32 s75, s11, 0
	s_add_u32 s78, s10, 0xf001300
	s_addc_u32 s79, s11, 0
	v_writelane_b32 v252, s14, 62
	s_cmp_eq_u32 s12, 15
	s_nop 0
	v_writelane_b32 v252, s15, 63
	s_cselect_b64 s[14:15], -1, 0
	v_writelane_b32 v253, s14, 0
	s_cmp_eq_u32 s12, 14
	s_nop 0
	v_writelane_b32 v253, s15, 1
	s_cselect_b64 s[14:15], -1, 0
	v_writelane_b32 v253, s14, 2
	s_cmp_eq_u32 s12, 13
	s_nop 0
	v_writelane_b32 v253, s15, 3
	s_cselect_b64 s[14:15], -1, 0
	v_writelane_b32 v253, s14, 4
	s_cmp_eq_u32 s12, 12
	s_nop 0
	v_writelane_b32 v253, s15, 5
	s_cselect_b64 s[14:15], -1, 0
	v_writelane_b32 v253, s14, 6
	s_cmp_eq_u32 s12, 11
	s_nop 0
	v_writelane_b32 v253, s15, 7
	s_cselect_b64 s[14:15], -1, 0
	v_writelane_b32 v253, s14, 8
	s_cmp_eq_u32 s12, 10
	s_nop 0
	v_writelane_b32 v253, s15, 9
	s_cselect_b64 s[14:15], -1, 0
	v_writelane_b32 v253, s14, 10
	s_cmp_eq_u32 s12, 9
	s_nop 0
	v_writelane_b32 v253, s15, 11
	s_cselect_b64 s[14:15], -1, 0
	v_writelane_b32 v253, s14, 12
	s_cmp_eq_u32 s12, 8
	s_nop 0
	v_writelane_b32 v253, s15, 13
	s_cselect_b64 s[14:15], -1, 0
	v_writelane_b32 v253, s14, 14
	s_cmp_eq_u32 s12, 7
	s_nop 0
	v_writelane_b32 v253, s15, 15
	s_mov_b64 s[14:15], 0x1400
	v_lshl_add_u64 v[218:219], v[0:1], 0, s[14:15]
	s_mov_b64 s[14:15], 0x2400
	v_lshl_add_u64 v[220:221], v[0:1], 0, s[14:15]
	s_cselect_b64 s[14:15], -1, 0
	v_writelane_b32 v253, s14, 16
	s_cmp_eq_u32 s12, 6
	s_nop 0
	v_writelane_b32 v253, s15, 17
	s_cselect_b64 s[14:15], -1, 0
	v_writelane_b32 v253, s14, 18
	s_cmp_eq_u32 s12, 5
	s_nop 0
	v_writelane_b32 v253, s15, 19
	s_cselect_b64 s[14:15], -1, 0
	v_writelane_b32 v253, s14, 20
	s_cmp_eq_u32 s12, 4
	s_nop 0
	v_writelane_b32 v253, s15, 21
	s_cselect_b64 s[14:15], -1, 0
	v_writelane_b32 v253, s14, 22
	s_cmp_eq_u32 s12, 3
	s_nop 0
	v_writelane_b32 v253, s15, 23
	s_cselect_b64 s[14:15], -1, 0
	v_writelane_b32 v253, s14, 24
	s_cmp_eq_u32 s12, 2
	s_nop 0
	v_writelane_b32 v253, s15, 25
	s_cselect_b64 s[14:15], -1, 0
	v_writelane_b32 v253, s14, 26
	s_cmp_eq_u32 s12, 1
	s_nop 0
	v_writelane_b32 v253, s15, 27
	s_cselect_b64 s[14:15], -1, 0
	v_writelane_b32 v253, s14, 28
	s_cmp_eq_u32 s12, 0
	s_nop 0
	v_writelane_b32 v253, s15, 29
	s_cselect_b64 s[14:15], -1, 0
	v_writelane_b32 v253, s14, 30
	s_nop 1
	v_writelane_b32 v253, s15, 31
	s_add_u32 s14, s10, 0xf003400
	s_addc_u32 s15, s11, 0
	v_writelane_b32 v253, s14, 32
	s_nop 1
	v_writelane_b32 v253, s15, 33
	s_add_u32 s14, s10, 0xf003500
	s_addc_u32 s15, s11, 0
	v_writelane_b32 v253, s14, 34
	s_add_u32 s12, s10, 0xef00000
	s_nop 0
	v_writelane_b32 v253, s15, 35
	v_writelane_b32 v253, s12, 36
	s_addc_u32 s12, s11, 0
	s_cmp_gt_i32 s2, 63
	v_writelane_b32 v253, s12, 37
	s_cselect_b64 s[14:15], -1, 0
	v_writelane_b32 v253, s14, 38
	s_add_i32 s12, s2, 0xffffff80
	s_nop 0
	v_writelane_b32 v253, s15, 39
	v_writelane_b32 v253, s12, 40
	s_sub_i32 s14, s2, 64
	s_add_i32 s12, s2, 0x80
	s_cmp_lt_u32 s55, 64
	v_writelane_b32 v253, s12, 41
	s_cselect_b64 s[16:17], -1, 0
	v_writelane_b32 v253, s16, 42
	v_readlane_b32 s12, v252, 32
	s_lshl_b32 s15, s12, 4
	v_writelane_b32 v253, s17, 43
	s_lshl_b32 s34, s12, 5
	s_add_i32 s12, s3, 0x1000
	v_writelane_b32 v253, s15, 44
	s_add_u32 s16, s10, 0x3600000
	v_writelane_b32 v253, s12, 45
	s_addc_u32 s17, s11, 0
	v_writelane_b32 v253, s16, 46
	s_nop 1
	v_writelane_b32 v253, s17, 47
	s_add_u32 s16, s10, 0x3700000
	s_addc_u32 s17, s11, 0
	v_writelane_b32 v253, s16, 48
	s_nop 1
	v_writelane_b32 v253, s17, 49
	s_add_u32 s16, s10, 0x3400000
	s_addc_u32 s17, s11, 0
	v_writelane_b32 v253, s16, 50
	s_add_u32 s12, s10, 0x5800000
	s_nop 0
	v_writelane_b32 v253, s17, 51
	v_writelane_b32 v253, s12, 52
	s_addc_u32 s12, s11, 0
	s_add_u32 s88, s10, 0xda00000
	s_addc_u32 s20, s11, 0
	s_add_u32 s16, s10, 0xec10000
	v_writelane_b32 v253, s12, 53
	s_addc_u32 s17, s11, 0
	v_writelane_b32 v253, s16, 54
	s_and_b32 s89, s20, 0xffff
	s_cmpk_lt_u32 s2, 0x40
	v_writelane_b32 v253, s17, 55
	v_writelane_b32 v253, s14, 56
	s_cselect_b64 s[14:15], -1, 0
	s_add_i32 s12, s2, 0xffffffc0
	s_nop 0
	v_writelane_b32 v253, s14, 57
	s_nop 0
	v_writelane_b32 v253, s15, 58
	s_add_u32 s14, s8, 0x6460000
	v_writelane_b32 v253, s12, 59
	s_addc_u32 s15, s9, 0
	v_writelane_b32 v253, s14, 60
	s_nop 1
	v_writelane_b32 v253, s15, 61
	s_add_u32 s14, s8, 0x4660000
	s_addc_u32 s15, s9, 0
	v_writelane_b32 v253, s14, 62
	s_nop 1
	v_writelane_b32 v253, s15, 63
	s_add_u32 s14, s8, 0x45e0000
	s_addc_u32 s15, s9, 0
	v_writelane_b32 v254, s14, 0
	s_nop 1
	v_writelane_b32 v254, s15, 1
	s_add_u32 s14, s8, 0x4400000
	s_addc_u32 s15, s9, 0
	s_add_u32 s35, s10, 0x5a01000
	v_writelane_b32 v254, s14, 2
	s_addc_u32 s36, s11, 0
	s_add_u32 s12, s10, 0x2400000
	v_writelane_b32 v254, s15, 3
	v_writelane_b32 v254, s12, 4
	s_addc_u32 s12, s11, 0
	s_cmpk_lt_i32 s2, 0x100
	v_writelane_b32 v254, s12, 5
	s_cselect_b64 s[14:15], -1, 0
	s_lshl_b32 s12, s6, 5
	s_add_u32 s19, s10, 0xda01000
	s_addc_u32 s21, s11, 0
	s_add_u32 s22, s10, 0xe400000
	s_addc_u32 s23, s11, 0
	v_writelane_b32 v254, s14, 6
	s_cmp_lt_i32 s2, 16
	s_nop 0
	v_writelane_b32 v254, s15, 7
	s_cselect_b64 s[14:15], -1, 0
	v_writelane_b32 v254, s14, 8
	s_lshl_b32 s38, s96, 4
	s_lshl_b32 s18, s6, 1
	v_writelane_b32 v254, s15, 9
	s_and_b32 s98, s2, 6
	s_lshl_b32 s98, s98, 3
	s_bfe_u32 s99, s2, 0x10005
	s_lshl_b32 s99, s99, 3
	s_or_b32 s98, s98, s99
	s_bfe_u32 s99, s2, 0x20003
	s_lshl_b32 s99, s99, 1
	s_or_b32 s98, s98, s99
	s_and_b32 s99, s2, 1
	s_or_b32 s98, s98, s99
	s_cmpk_lt_u32 s2, 0x40
	s_cselect_b32 s98, s98, s2
	s_lshr_b32 s14, s33, 28
	s_add_i32 s16, s98, s14
	s_ashr_i32 s17, s16, 4
	s_lshl_b32 s14, s17, 9
	s_ashr_i32 s15, s14, 31
	v_writelane_b32 v254, s19, 10
	s_lshl_b64 s[14:15], s[14:15], 1
	s_add_i32 s40, s38, 0xfffffc00
	v_writelane_b32 v254, s21, 11
	s_add_u32 s37, s19, s14
	v_writelane_b32 v254, s14, 12
	s_addc_u32 s39, s21, s15
	s_add_i32 s68, s17, -2
	v_writelane_b32 v254, s15, 13
	s_and_b32 s14, s16, -16
	s_sub_i32 s24, s98, s14
	s_lshl_b64 s[14:15], s[68:69], 21
	s_add_u32 s16, s22, s14
	v_writelane_b32 v254, s22, 14
	s_addc_u32 s17, s23, s15
	s_add_i32 s14, s98, 15
	s_cmp_lt_u32 s14, 31
	s_cselect_b32 s14, 0, 0x800
	v_writelane_b32 v254, s23, 15
	s_add_u32 s19, s88, s14
	v_writelane_b32 v254, s20, 16
	s_addc_u32 s20, s20, 0
	s_bfe_i32 s14, s24, 0x80000
	s_bfe_u32 s14, s14, 0x3000c
	s_add_i32 s14, s24, s14
	s_bfe_i32 s15, s14, 0x80000
	s_and_b32 s14, s14, 0xfff8
	s_sext_i32_i16 s15, s15
	s_sub_i32 s14, s24, s14
	s_ashr_i32 s15, s15, 3
	s_bfe_i32 s21, s14, 0x80000
	s_lshl_b32 s22, s14, 1
	v_writelane_b32 v254, s24, 17
	s_ashr_i32 s23, s24, 31
	v_writelane_b32 v254, s23, 18
	s_cmp_lt_i32 s6, 0
	s_mul_i32 s23, s6, 0x81
	s_cselect_b32 s7, s23, s7
	s_mul_i32 s23, s6, 33
	s_mul_i32 s6, s6, 3
	s_cselect_b32 s12, s23, s12
	s_cselect_b32 s18, s6, s18
	s_add_i32 s6, s7, s4
	s_ashr_i32 s7, s6, 31
	s_lshr_b32 s7, s7, 25
	s_add_i32 s7, s6, s7
	s_and_b32 s23, s7, 0xff80
	s_sub_i32 s6, s6, s23
	s_bfe_i32 s23, s6, 0x80000
	s_bfe_u32 s23, s23, 0x3000c
	s_add_i32 s23, s6, s23
	s_and_b32 s24, s23, 0xf8
	s_sub_i32 s6, s6, s24
	s_ashr_i32 s7, s7, 7
	s_bfe_i32 s23, s23, 0x80000
	s_lshl_b32 s7, s7, 3
	s_sext_i32_i16 s23, s23
	s_sext_i32_i8 s6, s6
	s_add_i32 s42, s7, s6
	s_ashr_i32 s6, s23, 3
	v_writelane_b32 v254, s6, 19
	s_lshr_b32 s6, s23, 3
	s_bfe_i64 s[6:7], s[6:7], 0x100000
	s_lshl_b64 s[6:7], s[6:7], 19
	v_writelane_b32 v254, s6, 20
	s_ashr_i32 s43, s42, 31
	s_mul_i32 s14, s14, 3
	v_writelane_b32 v254, s7, 21
	s_mov_b32 s6, s42
	v_writelane_b32 v254, s6, 22
	s_nop 1
	v_writelane_b32 v254, s7, 23
	s_lshl_b64 s[6:7], s[42:43], 19
	v_writelane_b32 v254, s25, 24
	s_add_u32 s6, s25, s6
	v_writelane_b32 v254, s26, 25
	s_addc_u32 s7, s26, s7
	s_add_u32 s24, s6, 0x40000
	v_writelane_b32 v254, s6, 26
	s_addc_u32 s25, s7, 0
	s_mov_b64 s[26:27], s[28:29]
	v_writelane_b32 v254, s7, 27
	s_add_i32 s6, s12, s4
	s_ashr_i32 s7, s6, 31
	s_lshr_b32 s7, s7, 27
	s_add_i32 s7, s6, s7
	s_and_b32 s12, s7, 0xffe0
	s_sub_i32 s6, s6, s12
	s_bfe_i32 s12, s6, 0x80000
	s_bfe_u32 s12, s12, 0x3000c
	s_add_i32 s12, s6, s12
	s_and_b32 s23, s12, 0xf8
	s_sub_i32 s6, s6, s23
	s_ashr_i32 s7, s7, 5
	s_bfe_i32 s12, s12, 0x80000
	v_writelane_b32 v254, s24, 28
	s_lshl_b32 s7, s7, 3
	s_sext_i32_i16 s12, s12
	s_sext_i32_i8 s6, s6
	v_writelane_b32 v254, s25, 29
	s_add_i32 s24, s7, s6
	s_ashr_i32 s6, s12, 3
	v_writelane_b32 v254, s6, 30
	s_lshr_b32 s6, s12, 3
	s_bfe_i64 s[6:7], s[6:7], 0x100000
	s_lshl_b64 s[6:7], s[6:7], 20
	v_writelane_b32 v254, s6, 31
	s_ashr_i32 s25, s24, 31
	s_mov_b32 s28, s69
	v_writelane_b32 v254, s7, 32
	s_mov_b32 s6, s24
	v_writelane_b32 v254, s6, 33
	s_nop 1
	v_writelane_b32 v254, s7, 34
	s_lshl_b64 s[6:7], s[24:25], 21
	s_add_u32 s6, s35, s6
	v_writelane_b32 v254, s35, 35
	s_addc_u32 s7, s36, s7
	v_writelane_b32 v254, s36, 36
	s_add_u32 s24, s6, 0x100000
	v_writelane_b32 v254, s6, 37
	s_addc_u32 s25, s7, 0
	s_add_i32 s4, s18, s4
	v_writelane_b32 v254, s7, 38
	s_ashr_i32 s6, s4, 31
	s_lshr_b32 s6, s6, 27
	s_add_i32 s6, s4, s6
	s_and_b32 s7, s6, 0xffffffe0
	s_ashr_i32 s6, s6, 5
	s_sub_i32 s23, s4, s7
	s_sext_i32_i16 s4, s21
	s_lshl_b32 s21, s6, 3
	v_writelane_b32 v254, s24, 39
	s_sub_i32 s6, 4, s21
	v_cvt_f32_i32_e32 v0, s23
	v_writelane_b32 v254, s25, 40
	s_min_u32 s24, s6, 8
	s_cmp_lt_i32 s4, 0
	s_cselect_b32 s4, s14, s22
	s_add_i32 s4, s4, s15
	s_bfe_i32 s6, s4, 0x80000
	s_bfe_u32 s6, s6, 0x2000d
	s_add_i32 s6, s4, s6
	s_bfe_i32 s7, s6, 0x80000
	s_sext_i32_i16 s12, s7
	s_and_b32 s6, s6, 0xfffc
	s_ashr_i32 s14, s12, 2
	s_lshr_b32 s12, s12, 2
	s_sub_i32 s4, s4, s6
	v_writelane_b32 v254, s14, 41
	s_bfe_i64 s[14:15], s[12:13], 0x100000
	s_bfe_i64 s[6:7], s[4:5], 0x80000
	s_lshl_b64 s[14:15], s[14:15], 20
	s_lshl_b64 s[6:7], s[6:7], 21
	v_writelane_b32 v254, s14, 42
	s_add_u32 s6, s37, s6
	s_addc_u32 s7, s39, s7
	v_writelane_b32 v254, s15, 43
	v_writelane_b32 v254, s37, 44
	v_writelane_b32 v254, s39, 45
	s_add_u32 s14, s6, 0x100000
	v_cvt_f32_ubyte0_e32 v1, s24
	v_writelane_b32 v254, s6, 46
	s_addc_u32 s15, s7, 0
	v_rcp_iflag_f32_e32 v2, v1
	s_cmp_lt_i32 s98, 32
	v_writelane_b32 v254, s7, 47
	s_cselect_b32 s6, s20, s17
	s_movk_i32 s7, 0x1000
	v_writelane_b32 v254, s14, 48
	s_cselect_b32 s12, s7, 0x400
	s_cselect_b32 s18, 13, 11
	s_cselect_b32 s92, s19, s16
	s_and_b32 s93, s6, 0xffff
	s_ashr_i32 s6, s23, 30
	v_writelane_b32 v254, s15, 49
	s_or_b32 s14, s6, 1
	v_mul_f32_e32 v2, v0, v2
	s_lshl_b32 s6, s12, 5
	v_trunc_f32_e32 v2, v2
	v_writelane_b32 v254, s6, 50
	v_fma_f32 v0, -v2, v1, v0
	v_writelane_b32 v254, s34, 51
	s_add_i32 s6, s34, 0
	v_writelane_b32 v254, s6, 52
	v_cmp_ge_f32_e64 s[6:7], |v0|, v1
	v_cvt_i32_f32_e32 v0, v2
	s_and_b64 s[6:7], s[6:7], exec
	s_sext_i32_i8 s4, s4
	v_writelane_b32 v254, s4, 53
	s_cselect_b32 s4, s14, 0
	v_readfirstlane_b32 s6, v0
	s_add_i32 s6, s6, s4
	s_mul_i32 s4, s6, s24
	s_sub_i32 s7, s23, s4
	s_sext_i32_i8 s7, s7
	s_add_i32 s14, s21, s7
	s_sext_i32_i8 s7, s6
	v_writelane_b32 v254, s7, 54
	s_bfe_i64 s[6:7], s[6:7], 0x80000
	s_lshl_b64 s[6:7], s[6:7], 20
	v_writelane_b32 v254, s6, 55
	s_ashr_i32 s15, s14, 31
	s_mov_b32 s4, s0
	v_writelane_b32 v254, s7, 56
	s_mul_i32 s6, s12, 0xc0
	v_writelane_b32 v254, s6, 57
	s_mov_b32 s6, s14
	v_writelane_b32 v254, s6, 58
	s_mov_b32 s12, 0xbfb8aa3b
	s_nop 0
	v_writelane_b32 v254, s7, 59
	s_lshl_b64 s[6:7], s[14:15], 21
	v_writelane_b32 v254, s6, 60
	s_mov_b64 s[14:15], 0xffffffff
	s_nop 0
	v_writelane_b32 v254, s7, 61
	s_add_u32 s6, s10, 0x5840080
	v_writelane_b32 v254, s6, 62
	s_addc_u32 s6, s11, 0
	v_writelane_b32 v254, s6, 63
	s_add_u32 s6, s10, 0x400100
	v_writelane_b32 v255, s6, 0
	s_addc_u32 s6, s11, 0
	s_ashr_i32 s39, s38, 31
	v_writelane_b32 v255, s6, 1
	s_add_i32 s6, s3, 0xfffbf800
	s_lshl_b64 s[70:71], s[38:39], 2
	v_writelane_b32 v255, s6, 2
	s_add_u32 s6, s8, 0x1000
	v_writelane_b32 v255, s6, 3
	s_addc_u32 s6, s9, 0
	v_writelane_b32 v255, s6, 4
	s_lshl_b32 s6, s2, 4
	s_addk_i32 s6, 0x3c00
	v_writelane_b32 v255, s6, 5
	s_add_i32 s6, 0, 0x20004
	v_writelane_b32 v255, s6, 6
	s_lshl_b64 s[6:7], s[38:39], 12
	v_writelane_b32 v255, s6, 7
	s_ashr_i32 s41, s40, 31
	s_lshl_b64 s[84:85], s[38:39], 11
	v_writelane_b32 v255, s7, 8
	s_mov_b32 s6, s38
	v_writelane_b32 v255, s6, 9
	s_nop 1
	v_writelane_b32 v255, s7, 10
	s_lshl_b64 s[6:7], s[38:39], 13
	v_writelane_b32 v255, s6, 11
	s_nop 1
	v_writelane_b32 v255, s7, 12
	s_lshl_b64 s[6:7], s[40:41], 2
	v_writelane_b32 v255, s6, 13
	s_nop 1
	v_writelane_b32 v255, s7, 14
	s_lshl_b64 s[6:7], s[40:41], 12
	v_writelane_b32 v255, s6, 15
	s_nop 1
	v_writelane_b32 v255, s7, 16
	s_lshl_b64 s[6:7], s[40:41], 11
	v_writelane_b32 v255, s6, 17
	s_nop 1
	v_writelane_b32 v255, s7, 18
	s_mov_b32 s6, s40
	v_writelane_b32 v255, s6, 19
	s_nop 1
	v_writelane_b32 v255, s7, 20
	s_lshl_b64 s[6:7], s[40:41], 13
	v_writelane_b32 v255, s6, 21
	s_nop 1
	v_writelane_b32 v255, s7, 22
	v_writelane_b32 v255, s62, 23
	s_nop 1
	v_writelane_b32 v255, s63, 24
	v_writelane_b32 v255, s26, 25
	s_nop 1
	v_writelane_b32 v255, s27, 26
	v_writelane_b32 v255, s80, 27
	s_nop 1
	v_writelane_b32 v255, s81, 28
	s_branch .LBB0_149

.LBB0_169:
	v_mbcnt_lo_u32_b32 v0, -1, 0
	v_mbcnt_hi_u32_b32 v0, -1, v0
	s_waitcnt vmcnt(0)
	s_nop 0
	v_sub_u32_e32 v0, 0, v0
	v_cmp_eq_u32_e32 vcc, s3, v0
	s_barrier
	s_and_saveexec_b64 s[6:7], vcc
	s_cbranch_execz .LBB0_217
	v_readlane_b32 s16, v255, 29
	s_mul_i32 s16, s16, 3
	s_add_i32 s17, s16, 1
	v_mov_b32_e32 v0, 0x20000
	v_readlane_b32 s21, v255, 6
	s_waitcnt vmcnt(0) lgkmcnt(0)
	ds_read_b32 v2, v0
	s_nop 1
	v_mov_b32_e32 v1, s21
	ds_read_b32 v3, v1
	global_atomic_add v1, v[218:219], v228, off offset:128 sc0
	s_waitcnt vmcnt(0) lgkmcnt(0)
	v_readfirstlane_b32 s21, v1
	v_readfirstlane_b32 s22, v2
	v_readfirstlane_b32 s23, v3
	s_add_i32 s21, s21, 1
	s_mul_i32 s22, s22, s17
	s_cmp_eq_u32 s21, s22
	s_cbranch_scc0 .Lxba_wait
	buffer_wbl2 sc1
	s_waitcnt vmcnt(0)
	s_add_u32 s36, s10, 0xf003480
	s_addc_u32 s37, s11, 0
	global_atomic_add v1, v161, v228, s[36:37] sc0
	s_waitcnt vmcnt(0)
	v_readfirstlane_b32 s21, v1
	s_add_i32 s21, s21, 1
	s_mul_i32 s23, s23, s17
	s_cmp_eq_u32 s21, s23
	s_cbranch_scc0 .Lxba_wait
	s_add_u32 s36, s10, 0xf002480
	s_addc_u32 s37, s11, 0
	global_atomic_add v161, v228, s[36:37]
	global_atomic_add v161, v228, s[36:37] offset:256
	global_atomic_add v161, v228, s[36:37] offset:512
	global_atomic_add v161, v228, s[36:37] offset:768
	global_atomic_add v161, v228, s[36:37] offset:1024
	global_atomic_add v161, v228, s[36:37] offset:1280
	global_atomic_add v161, v228, s[36:37] offset:1536
	global_atomic_add v161, v228, s[36:37] offset:1792
	global_atomic_add v161, v228, s[36:37] offset:2048
	global_atomic_add v161, v228, s[36:37] offset:2304
	global_atomic_add v161, v228, s[36:37] offset:2560
	global_atomic_add v161, v228, s[36:37] offset:2816
	global_atomic_add v161, v228, s[36:37] offset:3072
	global_atomic_add v161, v228, s[36:37] offset:3328
	global_atomic_add v161, v228, s[36:37] offset:3584
	global_atomic_add v161, v228, s[36:37] offset:3840
.Lxba_wait:
	s_mov_b32 s22, 0x4000
.Lxba_poll:
	global_load_dword v1, v[220:221], off offset:128 sc1
	s_waitcnt vmcnt(0)
	v_readfirstlane_b32 s21, v1
	s_cmp_ge_u32 s21, s17
	s_cbranch_scc1 .Lxba_seen
	s_sleep 1
	s_sub_u32 s22, s22, 1
	s_cmp_lg_u32 s22, 0
	s_cbranch_scc1 .Lxba_poll
.Lxba_seen:
	buffer_inv sc1
	s_waitcnt vmcnt(0)
.LBB0_217:
	s_or_b64 exec, exec, s[6:7]
	s_lshl_b32 s68, s28, 6
	s_lshl_b64 s[16:17], s[68:69], 2
	v_readlane_b32 s6, v253, 36
	s_add_u32 s94, s6, s16
	v_readlane_b32 s6, v253, 37
	v_writelane_b32 v255, s16, 31
	s_addc_u32 s95, s6, s17
	s_mov_b32 s21, s96
	s_waitcnt lgkmcnt(0)
	s_barrier
	s_cmpk_eq_i32 s21, 0x100
	v_writelane_b32 v255, s17, 32
	s_cselect_b64 s[6:7], -1, 0
	v_writelane_b32 v255, s6, 33
	s_cmpk_lg_i32 s21, 0x100
	s_cselect_b64 s[80:81], -1, 0
	v_writelane_b32 v255, s7, 34
	s_mul_hi_u32 s26, s28, 0x3000
	s_mul_i32 s27, s28, 0x3000
	s_lshl_b32 s60, s28, 3
	s_lshl_b64 s[6:7], s[28:29], 7
	s_lshl_b64 s[16:17], s[28:29], 14
	s_lshl_b64 s[22:23], s[28:29], 12
	s_lshl_b32 s61, s28, 2
	s_lshl_b64 s[28:29], s[28:29], 3
	s_sub_i32 s24, s21, s2
	v_writelane_b32 v255, s28, 35
	s_add_i32 s25, s24, 63
	v_readlane_b32 s36, v252, 16
	v_writelane_b32 v255, s29, 36
	v_readlane_b32 s28, v252, 34
	v_readlane_b32 s29, v252, 35
	s_add_u32 s72, s28, s27
	s_addc_u32 s73, s29, s26
	v_readlane_b32 s40, v252, 20
	v_readlane_b32 s41, v252, 21
	s_add_u32 s30, s40, s16
	v_readlane_b32 s42, v252, 22
	s_addc_u32 s31, s41, s17
	v_readlane_b32 s43, v252, 23
	s_add_u32 s64, s42, s22
	s_addc_u32 s65, s43, s23
	s_abs_i32 s16, s21
	v_cvt_f32_u32_e32 v0, s16
	s_sub_i32 s22, 0xffffffc1, s24
	s_xor_b32 s17, s25, s21
	s_max_i32 s23, s25, s22
	v_rcp_iflag_f32_e32 v0, v0
	s_sub_i32 s24, 0, s16
	s_ashr_i32 s17, s17, 31
	s_mov_b32 s22, 0
	v_mul_f32_e32 v0, 0x4f7ffffe, v0
	v_cvt_u32_f32_e32 v0, v0
	v_readlane_b32 s37, v252, 17
	v_readlane_b32 s38, v252, 18
	v_readlane_b32 s39, v252, 19
	v_readfirstlane_b32 s25, v0
	s_mul_i32 s24, s24, s25
	s_mul_hi_u32 s24, s25, s24
	s_add_i32 s25, s25, s24
	s_mul_hi_u32 s24, s23, s25
	s_mul_i32 s25, s24, s16
	s_sub_i32 s23, s23, s25
	s_add_i32 s25, s24, 1
	s_sub_i32 s26, s23, s16
	s_cmp_ge_u32 s23, s16
	s_cselect_b32 s24, s25, s24
	s_cselect_b32 s23, s26, s23
	s_add_i32 s25, s24, 1
	s_cmp_ge_u32 s23, s16
	s_cselect_b32 s16, s25, s24
	s_xor_b32 s16, s16, s17
	s_sub_i32 s23, s16, s17
	v_readlane_b32 s44, v252, 24
	v_readlane_b32 s45, v252, 25
	v_readlane_b32 s46, v252, 26
	v_readlane_b32 s47, v252, 27
	v_readlane_b32 s48, v252, 28
	v_readlane_b32 s49, v252, 29
	v_readlane_b32 s50, v252, 30
	v_readlane_b32 s51, v252, 31
	s_branch .LBB0_221

.LBB0_236:
	s_cmpk_lg_i32 s96, 0x100
	s_cbranch_scc1 .Lsch_keep
	s_mov_b32 s24, -1
	s_cmpk_lt_u32 s2, 0x40
	s_cbranch_scc0 .Lsch_nc
	s_cmp_eq_u32 s22, 0
	s_cbranch_scc0 .Lsch_c1
	s_mov_b32 s24, s2
	s_mov_b32 s25, 0
	s_branch .Lsch_keep
.Lsch_c1:
	s_cmp_lt_u32 s22, 5
	s_cbranch_scc0 .Lsch_c5
	s_lshl_b32 s25, s22, 8
	s_add_i32 s25, s25, 0x80
	s_add_i32 s25, s25, s2
	s_branch .Lsch_keep
.Lsch_c5:
	s_add_i32 s25, s2, 0x620
	s_cmp_eq_u32 s22, 5
	s_cselect_b32 s25, s25, 0x660
	s_branch .Lsch_keep
.Lsch_nc:
	s_cmp_lt_u32 s22, 2
	s_cbranch_scc0 .Lsch_n2
	s_mul_i32 s25, s22, 0xc0
	s_add_i32 s25, s25, s2
	s_sub_i32 s25, s25, 64
	s_branch .Lsch_keep
.Lsch_n2:
	s_cmp_lt_u32 s22, 5
	s_cbranch_scc0 .Lsch_n5
	s_lshl_b32 s25, s22, 8
	s_sub_i32 s25, s25, 0x80
	s_add_i32 s25, s25, s2
	s_branch .Lsch_keep
.Lsch_n5:
	s_cmpk_lt_u32 s2, 0xe0
	s_cbranch_scc0 .Lsch_s5
	s_add_i32 s25, s2, 0x480
	s_add_i32 s26, s2, 0x520
	s_cmp_eq_u32 s22, 6
	s_cselect_b32 s25, s26, s25
	s_cmp_lt_u32 s22, 7
	s_cselect_b32 s25, s25, 0x660
	s_branch .Lsch_keep
.Lsch_s5:
	s_add_i32 s25, s2, 0x520
	s_cmp_eq_u32 s22, 5
	s_cselect_b32 s25, s25, 0x660

.LBB0_294:
	s_andn2_b64 vcc, exec, s[16:17]
	s_cbranch_vccnz .LBB0_299
	s_movk_i32 s26, 0x1080
	v_lshlrev_b32_e32 v160, 1, v171
	v_mul_lo_u32 v103, v170, s26
	s_mov_b64 s[16:17], -1
	s_cmp_eq_u32 s38, 1
	v_lshlrev_b32_e32 v92, 2, v171
	v_add3_u32 v100, 0, v160, v103
	s_cbranch_scc1 .LBB0_297
	s_lshr_b32 s16, s40, 3
	v_add_u32_e32 v226, s16, v170
	v_readlane_b32 s48, v252, 4
	v_readlane_b32 s49, v252, 5
	v_lshlrev_b32_e32 v160, 1, v171
	v_lshlrev_b32_e32 v227, 3, v226
	v_add_u32_e32 v226, s6, v226
	v_mul_u32_u24_e32 v226, 0xf000, v226
	v_lshl_add_u32 v226, v171, 2, v226
	v_add_u32_e32 v229, 0x8000000, v160
	v_lshl_add_u32 v227, v227, 13, v229
	v_add_u32_e32 v212, 0xe000, v226
	global_load_dwordx4 v[64:67], v212, s[48:49] offset:0
	global_load_dwordx4 v[68:71], v212, s[48:49] offset:16
	global_load_dwordx4 v[172:175], v227, s[0:1] offset:0
	v_add_u32_e32 v213, 0x2000, v227
	global_load_dwordx4 v[176:179], v213, s[0:1] offset:0
	v_add_u32_e32 v214, 0x4000, v227
	global_load_dwordx4 v[180:183], v214, s[0:1] offset:0
	v_add_u32_e32 v215, 0x6000, v227
	global_load_dwordx4 v[184:187], v215, s[0:1] offset:0
	v_add_u32_e32 v212, 0x8000, v227
	global_load_dwordx4 v[188:191], v212, s[0:1] offset:0
	v_add_u32_e32 v213, 0xa000, v227
	global_load_dwordx4 v[192:195], v213, s[0:1] offset:0
	v_add_u32_e32 v214, 0xc000, v227
	global_load_dwordx4 v[196:199], v214, s[0:1] offset:0
	v_add_u32_e32 v215, 0xe000, v227
	global_load_dwordx4 v[200:203], v215, s[0:1] offset:0
	s_mov_b32 s44, 0xffff0000
	s_mov_b32 s45, 0x3f000000
	v_mul_u32_u24_e32 v229, 0x1080, v170
	v_add_u32_e32 v160, v229, v160
	v_mov_b64_e32 v[204:205], 0
	v_mov_b64_e32 v[206:207], 0
	v_mov_b64_e32 v[208:209], 0
	v_mov_b64_e32 v[210:211], 0
	s_waitcnt vmcnt(8)
	v_cvt_pk_bf16_f32 v64, v64, v65
	v_cvt_pk_bf16_f32 v65, v66, v67
	v_cvt_pk_bf16_f32 v66, v68, v69
	v_cvt_pk_bf16_f32 v67, v70, v71
	v_lshlrev_b32_e32 v212, 16, v64
	v_and_b32_e32 v213, s44, v64
	v_lshlrev_b32_e32 v214, 16, v65
	v_and_b32_e32 v215, s44, v65
	v_lshlrev_b32_e32 v216, 16, v66
	v_and_b32_e32 v217, s44, v66
	v_lshlrev_b32_e32 v222, 16, v67
	v_and_b32_e32 v223, s44, v67
	v_pk_add_f32 v[204:205], v[204:205], v[212:213]
	v_pk_add_f32 v[206:207], v[206:207], v[214:215]
	v_pk_add_f32 v[208:209], v[208:209], v[216:217]
	v_pk_add_f32 v[210:211], v[210:211], v[222:223]
	s_waitcnt vmcnt(7)
	v_lshlrev_b32_e32 v212, 16, v172
	v_and_b32_e32 v213, s44, v172
	v_lshlrev_b32_e32 v214, 16, v173
	v_and_b32_e32 v215, s44, v173
	v_lshlrev_b32_e32 v216, 16, v174
	v_and_b32_e32 v217, s44, v174
	v_lshlrev_b32_e32 v222, 16, v175
	v_and_b32_e32 v223, s44, v175
	v_pk_add_f32 v[204:205], v[204:205], v[212:213]
	v_pk_add_f32 v[206:207], v[206:207], v[214:215]
	v_pk_add_f32 v[208:209], v[208:209], v[216:217]
	v_pk_add_f32 v[210:211], v[210:211], v[222:223]
	v_fma_f32 v224, v204, s45, -v212
	v_fma_f32 v225, v205, s45, -v213
	v_cvt_pk_bf16_f32 v152, v224, v225
	v_fma_f32 v224, v206, s45, -v214
	v_fma_f32 v225, v207, s45, -v215
	v_cvt_pk_bf16_f32 v153, v224, v225
	v_fma_f32 v224, v208, s45, -v216
	v_fma_f32 v225, v209, s45, -v217
	v_cvt_pk_bf16_f32 v154, v224, v225
	v_fma_f32 v224, v210, s45, -v222
	v_fma_f32 v225, v211, s45, -v223
	v_cvt_pk_bf16_f32 v155, v224, v225
	ds_write_b128 v160, v[152:155]
	v_lshlrev_b32_e32 v212, 16, v64
	v_and_b32_e32 v213, s44, v64
	v_lshlrev_b32_e32 v214, 16, v65
	v_and_b32_e32 v215, s44, v65
	v_lshlrev_b32_e32 v216, 16, v66
	v_and_b32_e32 v217, s44, v66
	v_lshlrev_b32_e32 v222, 16, v67
	v_and_b32_e32 v223, s44, v67
	v_pk_add_f32 v[204:205], v[204:205], v[212:213] neg_lo:[0,1] neg_hi:[0,1]
	v_pk_add_f32 v[206:207], v[206:207], v[214:215] neg_lo:[0,1] neg_hi:[0,1]
	v_pk_add_f32 v[208:209], v[208:209], v[216:217] neg_lo:[0,1] neg_hi:[0,1]
	v_pk_add_f32 v[210:211], v[210:211], v[222:223] neg_lo:[0,1] neg_hi:[0,1]
	s_waitcnt vmcnt(6)
	v_lshlrev_b32_e32 v212, 16, v176
	v_and_b32_e32 v213, s44, v176
	v_lshlrev_b32_e32 v214, 16, v177
	v_and_b32_e32 v215, s44, v177
	v_lshlrev_b32_e32 v216, 16, v178
	v_and_b32_e32 v217, s44, v178
	v_lshlrev_b32_e32 v222, 16, v179
	v_and_b32_e32 v223, s44, v179
	v_pk_add_f32 v[204:205], v[204:205], v[212:213]
	v_pk_add_f32 v[206:207], v[206:207], v[214:215]
	v_pk_add_f32 v[208:209], v[208:209], v[216:217]
	v_pk_add_f32 v[210:211], v[210:211], v[222:223]
	v_fma_f32 v224, v204, s45, -v212
	v_fma_f32 v225, v205, s45, -v213
	v_cvt_pk_bf16_f32 v152, v224, v225
	v_fma_f32 v224, v206, s45, -v214
	v_fma_f32 v225, v207, s45, -v215
	v_cvt_pk_bf16_f32 v153, v224, v225
	v_fma_f32 v224, v208, s45, -v216
	v_fma_f32 v225, v209, s45, -v217
	v_cvt_pk_bf16_f32 v154, v224, v225
	v_fma_f32 v224, v210, s45, -v222
	v_fma_f32 v225, v211, s45, -v223
	v_cvt_pk_bf16_f32 v155, v224, v225
	ds_write_b128 v160, v[152:155] offset:528
	v_lshlrev_b32_e32 v212, 16, v172
	v_and_b32_e32 v213, s44, v172
	v_lshlrev_b32_e32 v214, 16, v173
	v_and_b32_e32 v215, s44, v173
	v_lshlrev_b32_e32 v216, 16, v174
	v_and_b32_e32 v217, s44, v174
	v_lshlrev_b32_e32 v222, 16, v175
	v_and_b32_e32 v223, s44, v175
	v_pk_add_f32 v[204:205], v[204:205], v[212:213] neg_lo:[0,1] neg_hi:[0,1]
	v_pk_add_f32 v[206:207], v[206:207], v[214:215] neg_lo:[0,1] neg_hi:[0,1]
	v_pk_add_f32 v[208:209], v[208:209], v[216:217] neg_lo:[0,1] neg_hi:[0,1]
	v_pk_add_f32 v[210:211], v[210:211], v[222:223] neg_lo:[0,1] neg_hi:[0,1]
	s_waitcnt vmcnt(5)
	v_lshlrev_b32_e32 v212, 16, v180
	v_and_b32_e32 v213, s44, v180
	v_lshlrev_b32_e32 v214, 16, v181
	v_and_b32_e32 v215, s44, v181
	v_lshlrev_b32_e32 v216, 16, v182
	v_and_b32_e32 v217, s44, v182
	v_lshlrev_b32_e32 v222, 16, v183
	v_and_b32_e32 v223, s44, v183
	v_pk_add_f32 v[204:205], v[204:205], v[212:213]
	v_pk_add_f32 v[206:207], v[206:207], v[214:215]
	v_pk_add_f32 v[208:209], v[208:209], v[216:217]
	v_pk_add_f32 v[210:211], v[210:211], v[222:223]
	v_fma_f32 v224, v204, s45, -v212
	v_fma_f32 v225, v205, s45, -v213
	v_cvt_pk_bf16_f32 v152, v224, v225
	v_fma_f32 v224, v206, s45, -v214
	v_fma_f32 v225, v207, s45, -v215
	v_cvt_pk_bf16_f32 v153, v224, v225
	v_fma_f32 v224, v208, s45, -v216
	v_fma_f32 v225, v209, s45, -v217
	v_cvt_pk_bf16_f32 v154, v224, v225
	v_fma_f32 v224, v210, s45, -v222
	v_fma_f32 v225, v211, s45, -v223
	v_cvt_pk_bf16_f32 v155, v224, v225
	ds_write_b128 v160, v[152:155] offset:1056
	v_lshlrev_b32_e32 v212, 16, v176
	v_and_b32_e32 v213, s44, v176
	v_lshlrev_b32_e32 v214, 16, v177
	v_and_b32_e32 v215, s44, v177
	v_lshlrev_b32_e32 v216, 16, v178
	v_and_b32_e32 v217, s44, v178
	v_lshlrev_b32_e32 v222, 16, v179
	v_and_b32_e32 v223, s44, v179
	v_pk_add_f32 v[204:205], v[204:205], v[212:213] neg_lo:[0,1] neg_hi:[0,1]
	v_pk_add_f32 v[206:207], v[206:207], v[214:215] neg_lo:[0,1] neg_hi:[0,1]
	v_pk_add_f32 v[208:209], v[208:209], v[216:217] neg_lo:[0,1] neg_hi:[0,1]
	v_pk_add_f32 v[210:211], v[210:211], v[222:223] neg_lo:[0,1] neg_hi:[0,1]
	s_waitcnt vmcnt(4)
	v_lshlrev_b32_e32 v212, 16, v184
	v_and_b32_e32 v213, s44, v184
	v_lshlrev_b32_e32 v214, 16, v185
	v_and_b32_e32 v215, s44, v185
	v_lshlrev_b32_e32 v216, 16, v186
	v_and_b32_e32 v217, s44, v186
	v_lshlrev_b32_e32 v222, 16, v187
	v_and_b32_e32 v223, s44, v187
	v_pk_add_f32 v[204:205], v[204:205], v[212:213]
	v_pk_add_f32 v[206:207], v[206:207], v[214:215]
	v_pk_add_f32 v[208:209], v[208:209], v[216:217]
	v_pk_add_f32 v[210:211], v[210:211], v[222:223]
	v_fma_f32 v224, v204, s45, -v212
	v_fma_f32 v225, v205, s45, -v213
	v_cvt_pk_bf16_f32 v152, v224, v225
	v_fma_f32 v224, v206, s45, -v214
	v_fma_f32 v225, v207, s45, -v215
	v_cvt_pk_bf16_f32 v153, v224, v225
	v_fma_f32 v224, v208, s45, -v216
	v_fma_f32 v225, v209, s45, -v217
	v_cvt_pk_bf16_f32 v154, v224, v225
	v_fma_f32 v224, v210, s45, -v222
	v_fma_f32 v225, v211, s45, -v223
	v_cvt_pk_bf16_f32 v155, v224, v225
	ds_write_b128 v160, v[152:155] offset:1584
	v_lshlrev_b32_e32 v212, 16, v180
	v_and_b32_e32 v213, s44, v180
	v_lshlrev_b32_e32 v214, 16, v181
	v_and_b32_e32 v215, s44, v181
	v_lshlrev_b32_e32 v216, 16, v182
	v_and_b32_e32 v217, s44, v182
	v_lshlrev_b32_e32 v222, 16, v183
	v_and_b32_e32 v223, s44, v183
	v_pk_add_f32 v[204:205], v[204:205], v[212:213] neg_lo:[0,1] neg_hi:[0,1]
	v_pk_add_f32 v[206:207], v[206:207], v[214:215] neg_lo:[0,1] neg_hi:[0,1]
	v_pk_add_f32 v[208:209], v[208:209], v[216:217] neg_lo:[0,1] neg_hi:[0,1]
	v_pk_add_f32 v[210:211], v[210:211], v[222:223] neg_lo:[0,1] neg_hi:[0,1]
	s_waitcnt vmcnt(3)
	v_lshlrev_b32_e32 v212, 16, v188
	v_and_b32_e32 v213, s44, v188
	v_lshlrev_b32_e32 v214, 16, v189
	v_and_b32_e32 v215, s44, v189
	v_lshlrev_b32_e32 v216, 16, v190
	v_and_b32_e32 v217, s44, v190
	v_lshlrev_b32_e32 v222, 16, v191
	v_and_b32_e32 v223, s44, v191
	v_pk_add_f32 v[204:205], v[204:205], v[212:213]
	v_pk_add_f32 v[206:207], v[206:207], v[214:215]
	v_pk_add_f32 v[208:209], v[208:209], v[216:217]
	v_pk_add_f32 v[210:211], v[210:211], v[222:223]
	v_fma_f32 v224, v204, s45, -v212
	v_fma_f32 v225, v205, s45, -v213
	v_cvt_pk_bf16_f32 v152, v224, v225
	v_fma_f32 v224, v206, s45, -v214
	v_fma_f32 v225, v207, s45, -v215
	v_cvt_pk_bf16_f32 v153, v224, v225
	v_fma_f32 v224, v208, s45, -v216
	v_fma_f32 v225, v209, s45, -v217
	v_cvt_pk_bf16_f32 v154, v224, v225
	v_fma_f32 v224, v210, s45, -v222
	v_fma_f32 v225, v211, s45, -v223
	v_cvt_pk_bf16_f32 v155, v224, v225
	ds_write_b128 v160, v[152:155] offset:2112
	v_lshlrev_b32_e32 v212, 16, v184
	v_and_b32_e32 v213, s44, v184
	v_lshlrev_b32_e32 v214, 16, v185
	v_and_b32_e32 v215, s44, v185
	v_lshlrev_b32_e32 v216, 16, v186
	v_and_b32_e32 v217, s44, v186
	v_lshlrev_b32_e32 v222, 16, v187
	v_and_b32_e32 v223, s44, v187
	v_pk_add_f32 v[204:205], v[204:205], v[212:213] neg_lo:[0,1] neg_hi:[0,1]
	v_pk_add_f32 v[206:207], v[206:207], v[214:215] neg_lo:[0,1] neg_hi:[0,1]
	v_pk_add_f32 v[208:209], v[208:209], v[216:217] neg_lo:[0,1] neg_hi:[0,1]
	v_pk_add_f32 v[210:211], v[210:211], v[222:223] neg_lo:[0,1] neg_hi:[0,1]
	s_waitcnt vmcnt(2)
	v_lshlrev_b32_e32 v212, 16, v192
	v_and_b32_e32 v213, s44, v192
	v_lshlrev_b32_e32 v214, 16, v193
	v_and_b32_e32 v215, s44, v193
	v_lshlrev_b32_e32 v216, 16, v194
	v_and_b32_e32 v217, s44, v194
	v_lshlrev_b32_e32 v222, 16, v195
	v_and_b32_e32 v223, s44, v195
	v_pk_add_f32 v[204:205], v[204:205], v[212:213]
	v_pk_add_f32 v[206:207], v[206:207], v[214:215]
	v_pk_add_f32 v[208:209], v[208:209], v[216:217]
	v_pk_add_f32 v[210:211], v[210:211], v[222:223]
	v_fma_f32 v224, v204, s45, -v212
	v_fma_f32 v225, v205, s45, -v213
	v_cvt_pk_bf16_f32 v152, v224, v225
	v_fma_f32 v224, v206, s45, -v214
	v_fma_f32 v225, v207, s45, -v215
	v_cvt_pk_bf16_f32 v153, v224, v225
	v_fma_f32 v224, v208, s45, -v216
	v_fma_f32 v225, v209, s45, -v217
	v_cvt_pk_bf16_f32 v154, v224, v225
	v_fma_f32 v224, v210, s45, -v222
	v_fma_f32 v225, v211, s45, -v223
	v_cvt_pk_bf16_f32 v155, v224, v225
	ds_write_b128 v160, v[152:155] offset:2640
	v_lshlrev_b32_e32 v212, 16, v188
	v_and_b32_e32 v213, s44, v188
	v_lshlrev_b32_e32 v214, 16, v189
	v_and_b32_e32 v215, s44, v189
	v_lshlrev_b32_e32 v216, 16, v190
	v_and_b32_e32 v217, s44, v190
	v_lshlrev_b32_e32 v222, 16, v191
	v_and_b32_e32 v223, s44, v191
	v_pk_add_f32 v[204:205], v[204:205], v[212:213] neg_lo:[0,1] neg_hi:[0,1]
	v_pk_add_f32 v[206:207], v[206:207], v[214:215] neg_lo:[0,1] neg_hi:[0,1]
	v_pk_add_f32 v[208:209], v[208:209], v[216:217] neg_lo:[0,1] neg_hi:[0,1]
	v_pk_add_f32 v[210:211], v[210:211], v[222:223] neg_lo:[0,1] neg_hi:[0,1]
	s_waitcnt vmcnt(1)
	v_lshlrev_b32_e32 v212, 16, v196
	v_and_b32_e32 v213, s44, v196
	v_lshlrev_b32_e32 v214, 16, v197
	v_and_b32_e32 v215, s44, v197
	v_lshlrev_b32_e32 v216, 16, v198
	v_and_b32_e32 v217, s44, v198
	v_lshlrev_b32_e32 v222, 16, v199
	v_and_b32_e32 v223, s44, v199
	v_pk_add_f32 v[204:205], v[204:205], v[212:213]
	v_pk_add_f32 v[206:207], v[206:207], v[214:215]
	v_pk_add_f32 v[208:209], v[208:209], v[216:217]
	v_pk_add_f32 v[210:211], v[210:211], v[222:223]
	v_fma_f32 v224, v204, s45, -v212
	v_fma_f32 v225, v205, s45, -v213
	v_cvt_pk_bf16_f32 v152, v224, v225
	v_fma_f32 v224, v206, s45, -v214
	v_fma_f32 v225, v207, s45, -v215
	v_cvt_pk_bf16_f32 v153, v224, v225
	v_fma_f32 v224, v208, s45, -v216
	v_fma_f32 v225, v209, s45, -v217
	v_cvt_pk_bf16_f32 v154, v224, v225
	v_fma_f32 v224, v210, s45, -v222
	v_fma_f32 v225, v211, s45, -v223
	v_cvt_pk_bf16_f32 v155, v224, v225
	ds_write_b128 v160, v[152:155] offset:3168
	v_lshlrev_b32_e32 v212, 16, v192
	v_and_b32_e32 v213, s44, v192
	v_lshlrev_b32_e32 v214, 16, v193
	v_and_b32_e32 v215, s44, v193
	v_lshlrev_b32_e32 v216, 16, v194
	v_and_b32_e32 v217, s44, v194
	v_lshlrev_b32_e32 v222, 16, v195
	v_and_b32_e32 v223, s44, v195
	v_pk_add_f32 v[204:205], v[204:205], v[212:213] neg_lo:[0,1] neg_hi:[0,1]
	v_pk_add_f32 v[206:207], v[206:207], v[214:215] neg_lo:[0,1] neg_hi:[0,1]
	v_pk_add_f32 v[208:209], v[208:209], v[216:217] neg_lo:[0,1] neg_hi:[0,1]
	v_pk_add_f32 v[210:211], v[210:211], v[222:223] neg_lo:[0,1] neg_hi:[0,1]
	s_waitcnt vmcnt(0)
	v_lshlrev_b32_e32 v212, 16, v200
	v_and_b32_e32 v213, s44, v200
	v_lshlrev_b32_e32 v214, 16, v201
	v_and_b32_e32 v215, s44, v201
	v_lshlrev_b32_e32 v216, 16, v202
	v_and_b32_e32 v217, s44, v202
	v_lshlrev_b32_e32 v222, 16, v203
	v_and_b32_e32 v223, s44, v203
	v_pk_add_f32 v[204:205], v[204:205], v[212:213]
	v_pk_add_f32 v[206:207], v[206:207], v[214:215]
	v_pk_add_f32 v[208:209], v[208:209], v[216:217]
	v_pk_add_f32 v[210:211], v[210:211], v[222:223]
	v_fma_f32 v224, v204, s45, -v212
	v_fma_f32 v225, v205, s45, -v213
	v_cvt_pk_bf16_f32 v64, v224, v225
	v_fma_f32 v224, v206, s45, -v214
	v_fma_f32 v225, v207, s45, -v215
	v_cvt_pk_bf16_f32 v65, v224, v225
	v_fma_f32 v224, v208, s45, -v216
	v_fma_f32 v225, v209, s45, -v217
	v_cvt_pk_bf16_f32 v66, v224, v225
	v_fma_f32 v224, v210, s45, -v222
	v_fma_f32 v225, v211, s45, -v223
	v_cvt_pk_bf16_f32 v67, v224, v225
	v_mov_b32_e32 v96, v160
	s_mov_b64 s[16:17], 0
.LBB0_297:
	s_andn2_b64 vcc, exec, s[16:17]
	s_cbranch_vccnz .LBB0_299
	s_lshr_b32 s16, s40, 3
	v_add_u32_e32 v226, s16, v170
	v_readlane_b32 s48, v252, 4
	v_readlane_b32 s49, v252, 5
	v_lshlrev_b32_e32 v160, 1, v171
	v_lshlrev_b32_e32 v227, 3, v226
	v_add_u32_e32 v226, s6, v226
	v_mul_u32_u24_e32 v226, 0xf000, v226
	v_lshl_add_u32 v226, v171, 2, v226
	v_add_u32_e32 v229, 0x8000000, v160
	v_lshl_add_u32 v227, v227, 13, v229
	v_add_u32_e32 v212, 0xc000, v226
	global_load_dwordx4 v[64:67], v212, s[48:49] offset:1024
	global_load_dwordx4 v[68:71], v212, s[48:49] offset:1040
	v_add_u32_e32 v213, 0xd000, v226
	global_load_dwordx4 v[72:75], v213, s[48:49] offset:1024
	global_load_dwordx4 v[76:79], v213, s[48:49] offset:1040
	v_add_u32_e32 v214, 0xe000, v226
	global_load_dwordx4 v[80:83], v214, s[48:49] offset:1024
	global_load_dwordx4 v[84:87], v214, s[48:49] offset:1040
	global_load_dwordx4 v[172:175], v227, s[0:1] offset:512
	v_add_u32_e32 v213, 0x2000, v227
	global_load_dwordx4 v[176:179], v213, s[0:1] offset:512
	v_add_u32_e32 v214, 0x4000, v227
	global_load_dwordx4 v[180:183], v214, s[0:1] offset:512
	v_add_u32_e32 v215, 0x6000, v227
	global_load_dwordx4 v[184:187], v215, s[0:1] offset:512
	v_add_u32_e32 v212, 0x8000, v227
	global_load_dwordx4 v[188:191], v212, s[0:1] offset:512
	v_add_u32_e32 v213, 0xa000, v227
	global_load_dwordx4 v[192:195], v213, s[0:1] offset:512
	v_add_u32_e32 v214, 0xc000, v227
	global_load_dwordx4 v[196:199], v214, s[0:1] offset:512
	v_add_u32_e32 v215, 0xe000, v227
	global_load_dwordx4 v[200:203], v215, s[0:1] offset:512
	s_mov_b32 s44, 0xffff0000
	s_mov_b32 s45, 0x3e800000
	v_mul_u32_u24_e32 v229, 0x1080, v170
	v_add_u32_e32 v160, v229, v160
	v_mov_b64_e32 v[204:205], 0
	v_mov_b64_e32 v[206:207], 0
	v_mov_b64_e32 v[208:209], 0
	v_mov_b64_e32 v[210:211], 0
	s_waitcnt vmcnt(12)
	v_cvt_pk_bf16_f32 v64, v64, v65
	v_cvt_pk_bf16_f32 v65, v66, v67
	v_cvt_pk_bf16_f32 v66, v68, v69
	v_cvt_pk_bf16_f32 v67, v70, v71
	v_lshlrev_b32_e32 v212, 16, v64
	v_and_b32_e32 v213, s44, v64
	v_lshlrev_b32_e32 v214, 16, v65
	v_and_b32_e32 v215, s44, v65
	v_lshlrev_b32_e32 v216, 16, v66
	v_and_b32_e32 v217, s44, v66
	v_lshlrev_b32_e32 v222, 16, v67
	v_and_b32_e32 v223, s44, v67
	v_pk_add_f32 v[204:205], v[204:205], v[212:213]
	v_pk_add_f32 v[206:207], v[206:207], v[214:215]
	v_pk_add_f32 v[208:209], v[208:209], v[216:217]
	v_pk_add_f32 v[210:211], v[210:211], v[222:223]
	s_waitcnt vmcnt(10)
	v_cvt_pk_bf16_f32 v72, v72, v73
	v_cvt_pk_bf16_f32 v73, v74, v75
	v_cvt_pk_bf16_f32 v74, v76, v77
	v_cvt_pk_bf16_f32 v75, v78, v79
	v_lshlrev_b32_e32 v212, 16, v72
	v_and_b32_e32 v213, s44, v72
	v_lshlrev_b32_e32 v214, 16, v73
	v_and_b32_e32 v215, s44, v73
	v_lshlrev_b32_e32 v216, 16, v74
	v_and_b32_e32 v217, s44, v74
	v_lshlrev_b32_e32 v222, 16, v75
	v_and_b32_e32 v223, s44, v75
	v_pk_add_f32 v[204:205], v[204:205], v[212:213]
	v_pk_add_f32 v[206:207], v[206:207], v[214:215]
	v_pk_add_f32 v[208:209], v[208:209], v[216:217]
	v_pk_add_f32 v[210:211], v[210:211], v[222:223]
	s_waitcnt vmcnt(8)
	v_cvt_pk_bf16_f32 v80, v80, v81
	v_cvt_pk_bf16_f32 v81, v82, v83
	v_cvt_pk_bf16_f32 v82, v84, v85
	v_cvt_pk_bf16_f32 v83, v86, v87
	v_lshlrev_b32_e32 v212, 16, v80
	v_and_b32_e32 v213, s44, v80
	v_lshlrev_b32_e32 v214, 16, v81
	v_and_b32_e32 v215, s44, v81
	v_lshlrev_b32_e32 v216, 16, v82
	v_and_b32_e32 v217, s44, v82
	v_lshlrev_b32_e32 v222, 16, v83
	v_and_b32_e32 v223, s44, v83
	v_pk_add_f32 v[204:205], v[204:205], v[212:213]
	v_pk_add_f32 v[206:207], v[206:207], v[214:215]
	v_pk_add_f32 v[208:209], v[208:209], v[216:217]
	v_pk_add_f32 v[210:211], v[210:211], v[222:223]
	s_waitcnt vmcnt(7)
	v_lshlrev_b32_e32 v212, 16, v172
	v_and_b32_e32 v213, s44, v172
	v_lshlrev_b32_e32 v214, 16, v173
	v_and_b32_e32 v215, s44, v173
	v_lshlrev_b32_e32 v216, 16, v174
	v_and_b32_e32 v217, s44, v174
	v_lshlrev_b32_e32 v222, 16, v175
	v_and_b32_e32 v223, s44, v175
	v_pk_add_f32 v[204:205], v[204:205], v[212:213]
	v_pk_add_f32 v[206:207], v[206:207], v[214:215]
	v_pk_add_f32 v[208:209], v[208:209], v[216:217]
	v_pk_add_f32 v[210:211], v[210:211], v[222:223]
	v_fma_f32 v224, v204, s45, -v212
	v_fma_f32 v225, v205, s45, -v213
	v_cvt_pk_bf16_f32 v152, v224, v225
	v_fma_f32 v224, v206, s45, -v214
	v_fma_f32 v225, v207, s45, -v215
	v_cvt_pk_bf16_f32 v153, v224, v225
	v_fma_f32 v224, v208, s45, -v216
	v_fma_f32 v225, v209, s45, -v217
	v_cvt_pk_bf16_f32 v154, v224, v225
	v_fma_f32 v224, v210, s45, -v222
	v_fma_f32 v225, v211, s45, -v223
	v_cvt_pk_bf16_f32 v155, v224, v225
	ds_write_b128 v160, v[152:155]
	v_lshlrev_b32_e32 v212, 16, v64
	v_and_b32_e32 v213, s44, v64
	v_lshlrev_b32_e32 v214, 16, v65
	v_and_b32_e32 v215, s44, v65
	v_lshlrev_b32_e32 v216, 16, v66
	v_and_b32_e32 v217, s44, v66
	v_lshlrev_b32_e32 v222, 16, v67
	v_and_b32_e32 v223, s44, v67
	v_pk_add_f32 v[204:205], v[204:205], v[212:213] neg_lo:[0,1] neg_hi:[0,1]
	v_pk_add_f32 v[206:207], v[206:207], v[214:215] neg_lo:[0,1] neg_hi:[0,1]
	v_pk_add_f32 v[208:209], v[208:209], v[216:217] neg_lo:[0,1] neg_hi:[0,1]
	v_pk_add_f32 v[210:211], v[210:211], v[222:223] neg_lo:[0,1] neg_hi:[0,1]
	s_waitcnt vmcnt(6)
	v_lshlrev_b32_e32 v212, 16, v176
	v_and_b32_e32 v213, s44, v176
	v_lshlrev_b32_e32 v214, 16, v177
	v_and_b32_e32 v215, s44, v177
	v_lshlrev_b32_e32 v216, 16, v178
	v_and_b32_e32 v217, s44, v178
	v_lshlrev_b32_e32 v222, 16, v179
	v_and_b32_e32 v223, s44, v179
	v_pk_add_f32 v[204:205], v[204:205], v[212:213]
	v_pk_add_f32 v[206:207], v[206:207], v[214:215]
	v_pk_add_f32 v[208:209], v[208:209], v[216:217]
	v_pk_add_f32 v[210:211], v[210:211], v[222:223]
	v_fma_f32 v224, v204, s45, -v212
	v_fma_f32 v225, v205, s45, -v213
	v_cvt_pk_bf16_f32 v152, v224, v225
	v_fma_f32 v224, v206, s45, -v214
	v_fma_f32 v225, v207, s45, -v215
	v_cvt_pk_bf16_f32 v153, v224, v225
	v_fma_f32 v224, v208, s45, -v216
	v_fma_f32 v225, v209, s45, -v217
	v_cvt_pk_bf16_f32 v154, v224, v225
	v_fma_f32 v224, v210, s45, -v222
	v_fma_f32 v225, v211, s45, -v223
	v_cvt_pk_bf16_f32 v155, v224, v225
	ds_write_b128 v160, v[152:155] offset:528
	v_lshlrev_b32_e32 v212, 16, v72
	v_and_b32_e32 v213, s44, v72
	v_lshlrev_b32_e32 v214, 16, v73
	v_and_b32_e32 v215, s44, v73
	v_lshlrev_b32_e32 v216, 16, v74
	v_and_b32_e32 v217, s44, v74
	v_lshlrev_b32_e32 v222, 16, v75
	v_and_b32_e32 v223, s44, v75
	v_pk_add_f32 v[204:205], v[204:205], v[212:213] neg_lo:[0,1] neg_hi:[0,1]
	v_pk_add_f32 v[206:207], v[206:207], v[214:215] neg_lo:[0,1] neg_hi:[0,1]
	v_pk_add_f32 v[208:209], v[208:209], v[216:217] neg_lo:[0,1] neg_hi:[0,1]
	v_pk_add_f32 v[210:211], v[210:211], v[222:223] neg_lo:[0,1] neg_hi:[0,1]
	s_waitcnt vmcnt(5)
	v_lshlrev_b32_e32 v212, 16, v180
	v_and_b32_e32 v213, s44, v180
	v_lshlrev_b32_e32 v214, 16, v181
	v_and_b32_e32 v215, s44, v181
	v_lshlrev_b32_e32 v216, 16, v182
	v_and_b32_e32 v217, s44, v182
	v_lshlrev_b32_e32 v222, 16, v183
	v_and_b32_e32 v223, s44, v183
	v_pk_add_f32 v[204:205], v[204:205], v[212:213]
	v_pk_add_f32 v[206:207], v[206:207], v[214:215]
	v_pk_add_f32 v[208:209], v[208:209], v[216:217]
	v_pk_add_f32 v[210:211], v[210:211], v[222:223]
	v_fma_f32 v224, v204, s45, -v212
	v_fma_f32 v225, v205, s45, -v213
	v_cvt_pk_bf16_f32 v152, v224, v225
	v_fma_f32 v224, v206, s45, -v214
	v_fma_f32 v225, v207, s45, -v215
	v_cvt_pk_bf16_f32 v153, v224, v225
	v_fma_f32 v224, v208, s45, -v216
	v_fma_f32 v225, v209, s45, -v217
	v_cvt_pk_bf16_f32 v154, v224, v225
	v_fma_f32 v224, v210, s45, -v222
	v_fma_f32 v225, v211, s45, -v223
	v_cvt_pk_bf16_f32 v155, v224, v225
	ds_write_b128 v160, v[152:155] offset:1056
	v_lshlrev_b32_e32 v212, 16, v80
	v_and_b32_e32 v213, s44, v80
	v_lshlrev_b32_e32 v214, 16, v81
	v_and_b32_e32 v215, s44, v81
	v_lshlrev_b32_e32 v216, 16, v82
	v_and_b32_e32 v217, s44, v82
	v_lshlrev_b32_e32 v222, 16, v83
	v_and_b32_e32 v223, s44, v83
	v_pk_add_f32 v[204:205], v[204:205], v[212:213] neg_lo:[0,1] neg_hi:[0,1]
	v_pk_add_f32 v[206:207], v[206:207], v[214:215] neg_lo:[0,1] neg_hi:[0,1]
	v_pk_add_f32 v[208:209], v[208:209], v[216:217] neg_lo:[0,1] neg_hi:[0,1]
	v_pk_add_f32 v[210:211], v[210:211], v[222:223] neg_lo:[0,1] neg_hi:[0,1]
	s_waitcnt vmcnt(4)
	v_lshlrev_b32_e32 v212, 16, v184
	v_and_b32_e32 v213, s44, v184
	v_lshlrev_b32_e32 v214, 16, v185
	v_and_b32_e32 v215, s44, v185
	v_lshlrev_b32_e32 v216, 16, v186
	v_and_b32_e32 v217, s44, v186
	v_lshlrev_b32_e32 v222, 16, v187
	v_and_b32_e32 v223, s44, v187
	v_pk_add_f32 v[204:205], v[204:205], v[212:213]
	v_pk_add_f32 v[206:207], v[206:207], v[214:215]
	v_pk_add_f32 v[208:209], v[208:209], v[216:217]
	v_pk_add_f32 v[210:211], v[210:211], v[222:223]
	v_fma_f32 v224, v204, s45, -v212
	v_fma_f32 v225, v205, s45, -v213
	v_cvt_pk_bf16_f32 v152, v224, v225
	v_fma_f32 v224, v206, s45, -v214
	v_fma_f32 v225, v207, s45, -v215
	v_cvt_pk_bf16_f32 v153, v224, v225
	v_fma_f32 v224, v208, s45, -v216
	v_fma_f32 v225, v209, s45, -v217
	v_cvt_pk_bf16_f32 v154, v224, v225
	v_fma_f32 v224, v210, s45, -v222
	v_fma_f32 v225, v211, s45, -v223
	v_cvt_pk_bf16_f32 v155, v224, v225
	ds_write_b128 v160, v[152:155] offset:1584
	v_lshlrev_b32_e32 v212, 16, v172
	v_and_b32_e32 v213, s44, v172
	v_lshlrev_b32_e32 v214, 16, v173
	v_and_b32_e32 v215, s44, v173
	v_lshlrev_b32_e32 v216, 16, v174
	v_and_b32_e32 v217, s44, v174
	v_lshlrev_b32_e32 v222, 16, v175
	v_and_b32_e32 v223, s44, v175
	v_pk_add_f32 v[204:205], v[204:205], v[212:213] neg_lo:[0,1] neg_hi:[0,1]
	v_pk_add_f32 v[206:207], v[206:207], v[214:215] neg_lo:[0,1] neg_hi:[0,1]
	v_pk_add_f32 v[208:209], v[208:209], v[216:217] neg_lo:[0,1] neg_hi:[0,1]
	v_pk_add_f32 v[210:211], v[210:211], v[222:223] neg_lo:[0,1] neg_hi:[0,1]
	s_waitcnt vmcnt(3)
	v_lshlrev_b32_e32 v212, 16, v188
	v_and_b32_e32 v213, s44, v188
	v_lshlrev_b32_e32 v214, 16, v189
	v_and_b32_e32 v215, s44, v189
	v_lshlrev_b32_e32 v216, 16, v190
	v_and_b32_e32 v217, s44, v190
	v_lshlrev_b32_e32 v222, 16, v191
	v_and_b32_e32 v223, s44, v191
	v_pk_add_f32 v[204:205], v[204:205], v[212:213]
	v_pk_add_f32 v[206:207], v[206:207], v[214:215]
	v_pk_add_f32 v[208:209], v[208:209], v[216:217]
	v_pk_add_f32 v[210:211], v[210:211], v[222:223]
	v_fma_f32 v224, v204, s45, -v212
	v_fma_f32 v225, v205, s45, -v213
	v_cvt_pk_bf16_f32 v152, v224, v225
	v_fma_f32 v224, v206, s45, -v214
	v_fma_f32 v225, v207, s45, -v215
	v_cvt_pk_bf16_f32 v153, v224, v225
	v_fma_f32 v224, v208, s45, -v216
	v_fma_f32 v225, v209, s45, -v217
	v_cvt_pk_bf16_f32 v154, v224, v225
	v_fma_f32 v224, v210, s45, -v222
	v_fma_f32 v225, v211, s45, -v223
	v_cvt_pk_bf16_f32 v155, v224, v225
	ds_write_b128 v160, v[152:155] offset:2112
	v_lshlrev_b32_e32 v212, 16, v176
	v_and_b32_e32 v213, s44, v176
	v_lshlrev_b32_e32 v214, 16, v177
	v_and_b32_e32 v215, s44, v177
	v_lshlrev_b32_e32 v216, 16, v178
	v_and_b32_e32 v217, s44, v178
	v_lshlrev_b32_e32 v222, 16, v179
	v_and_b32_e32 v223, s44, v179
	v_pk_add_f32 v[204:205], v[204:205], v[212:213] neg_lo:[0,1] neg_hi:[0,1]
	v_pk_add_f32 v[206:207], v[206:207], v[214:215] neg_lo:[0,1] neg_hi:[0,1]
	v_pk_add_f32 v[208:209], v[208:209], v[216:217] neg_lo:[0,1] neg_hi:[0,1]
	v_pk_add_f32 v[210:211], v[210:211], v[222:223] neg_lo:[0,1] neg_hi:[0,1]
	s_waitcnt vmcnt(2)
	v_lshlrev_b32_e32 v212, 16, v192
	v_and_b32_e32 v213, s44, v192
	v_lshlrev_b32_e32 v214, 16, v193
	v_and_b32_e32 v215, s44, v193
	v_lshlrev_b32_e32 v216, 16, v194
	v_and_b32_e32 v217, s44, v194
	v_lshlrev_b32_e32 v222, 16, v195
	v_and_b32_e32 v223, s44, v195
	v_pk_add_f32 v[204:205], v[204:205], v[212:213]
	v_pk_add_f32 v[206:207], v[206:207], v[214:215]
	v_pk_add_f32 v[208:209], v[208:209], v[216:217]
	v_pk_add_f32 v[210:211], v[210:211], v[222:223]
	v_fma_f32 v224, v204, s45, -v212
	v_fma_f32 v225, v205, s45, -v213
	v_cvt_pk_bf16_f32 v152, v224, v225
	v_fma_f32 v224, v206, s45, -v214
	v_fma_f32 v225, v207, s45, -v215
	v_cvt_pk_bf16_f32 v153, v224, v225
	v_fma_f32 v224, v208, s45, -v216
	v_fma_f32 v225, v209, s45, -v217
	v_cvt_pk_bf16_f32 v154, v224, v225
	v_fma_f32 v224, v210, s45, -v222
	v_fma_f32 v225, v211, s45, -v223
	v_cvt_pk_bf16_f32 v155, v224, v225
	ds_write_b128 v160, v[152:155] offset:2640
	v_lshlrev_b32_e32 v212, 16, v180
	v_and_b32_e32 v213, s44, v180
	v_lshlrev_b32_e32 v214, 16, v181
	v_and_b32_e32 v215, s44, v181
	v_lshlrev_b32_e32 v216, 16, v182
	v_and_b32_e32 v217, s44, v182
	v_lshlrev_b32_e32 v222, 16, v183
	v_and_b32_e32 v223, s44, v183
	v_pk_add_f32 v[204:205], v[204:205], v[212:213] neg_lo:[0,1] neg_hi:[0,1]
	v_pk_add_f32 v[206:207], v[206:207], v[214:215] neg_lo:[0,1] neg_hi:[0,1]
	v_pk_add_f32 v[208:209], v[208:209], v[216:217] neg_lo:[0,1] neg_hi:[0,1]
	v_pk_add_f32 v[210:211], v[210:211], v[222:223] neg_lo:[0,1] neg_hi:[0,1]
	s_waitcnt vmcnt(1)
	v_lshlrev_b32_e32 v212, 16, v196
	v_and_b32_e32 v213, s44, v196
	v_lshlrev_b32_e32 v214, 16, v197
	v_and_b32_e32 v215, s44, v197
	v_lshlrev_b32_e32 v216, 16, v198
	v_and_b32_e32 v217, s44, v198
	v_lshlrev_b32_e32 v222, 16, v199
	v_and_b32_e32 v223, s44, v199
	v_pk_add_f32 v[204:205], v[204:205], v[212:213]
	v_pk_add_f32 v[206:207], v[206:207], v[214:215]
	v_pk_add_f32 v[208:209], v[208:209], v[216:217]
	v_pk_add_f32 v[210:211], v[210:211], v[222:223]
	v_fma_f32 v224, v204, s45, -v212
	v_fma_f32 v225, v205, s45, -v213
	v_cvt_pk_bf16_f32 v152, v224, v225
	v_fma_f32 v224, v206, s45, -v214
	v_fma_f32 v225, v207, s45, -v215
	v_cvt_pk_bf16_f32 v153, v224, v225
	v_fma_f32 v224, v208, s45, -v216
	v_fma_f32 v225, v209, s45, -v217
	v_cvt_pk_bf16_f32 v154, v224, v225
	v_fma_f32 v224, v210, s45, -v222
	v_fma_f32 v225, v211, s45, -v223
	v_cvt_pk_bf16_f32 v155, v224, v225
	ds_write_b128 v160, v[152:155] offset:3168
	v_lshlrev_b32_e32 v212, 16, v184
	v_and_b32_e32 v213, s44, v184
	v_lshlrev_b32_e32 v214, 16, v185
	v_and_b32_e32 v215, s44, v185
	v_lshlrev_b32_e32 v216, 16, v186
	v_and_b32_e32 v217, s44, v186
	v_lshlrev_b32_e32 v222, 16, v187
	v_and_b32_e32 v223, s44, v187
	v_pk_add_f32 v[204:205], v[204:205], v[212:213] neg_lo:[0,1] neg_hi:[0,1]
	v_pk_add_f32 v[206:207], v[206:207], v[214:215] neg_lo:[0,1] neg_hi:[0,1]
	v_pk_add_f32 v[208:209], v[208:209], v[216:217] neg_lo:[0,1] neg_hi:[0,1]
	v_pk_add_f32 v[210:211], v[210:211], v[222:223] neg_lo:[0,1] neg_hi:[0,1]
	s_waitcnt vmcnt(0)
	v_lshlrev_b32_e32 v212, 16, v200
	v_and_b32_e32 v213, s44, v200
	v_lshlrev_b32_e32 v214, 16, v201
	v_and_b32_e32 v215, s44, v201
	v_lshlrev_b32_e32 v216, 16, v202
	v_and_b32_e32 v217, s44, v202
	v_lshlrev_b32_e32 v222, 16, v203
	v_and_b32_e32 v223, s44, v203
	v_pk_add_f32 v[204:205], v[204:205], v[212:213]
	v_pk_add_f32 v[206:207], v[206:207], v[214:215]
	v_pk_add_f32 v[208:209], v[208:209], v[216:217]
	v_pk_add_f32 v[210:211], v[210:211], v[222:223]
	v_fma_f32 v224, v204, s45, -v212
	v_fma_f32 v225, v205, s45, -v213
	v_cvt_pk_bf16_f32 v64, v224, v225
	v_fma_f32 v224, v206, s45, -v214
	v_fma_f32 v225, v207, s45, -v215
	v_cvt_pk_bf16_f32 v65, v224, v225
	v_fma_f32 v224, v208, s45, -v216
	v_fma_f32 v225, v209, s45, -v217
	v_cvt_pk_bf16_f32 v66, v224, v225
	v_fma_f32 v224, v210, s45, -v222
	v_fma_f32 v225, v211, s45, -v223
	v_cvt_pk_bf16_f32 v67, v224, v225
	v_mov_b32_e32 v96, v160
	s_mov_b64 s[16:17], 0

.LBB0_386:
	v_readlane_b32 s16, v253, 57
	v_readlane_b32 s17, v253, 58
	s_and_b64 s[16:17], s[16:17], s[24:25]
	s_and_b64 vcc, exec, s[16:17]
	s_barrier
	s_cbranch_vccnz .LBB0_461
	s_and_b64 s[16:17], s[24:25], exec
	v_readlane_b32 s16, v253, 59
	s_cselect_b32 s16, s16, s2
	s_lshl_b32 s16, s16, 9
	s_add_i32 s17, s16, s3
	v_add_u32_e32 v1, s17, v0
	s_mov_b32 s17, 0x4c800
	v_cmp_gt_i32_e32 vcc, s17, v1
	s_and_saveexec_b64 s[42:43], vcc
	v_readlane_b32 s28, v255, 35
	v_readlane_b32 s29, v255, 36
	s_cbranch_execz .LBB0_460
	s_lshl_b32 s17, s21, 9
	s_and_b64 s[20:21], s[24:25], exec
	s_cselect_b32 s19, 0x18000, s17
	v_readlane_b32 s17, v255, 2
	s_add_i32 s16, s16, s17
	v_add_u32_e32 v38, s16, v0
	s_lshl_b32 s20, s19, 1
	v_lshlrev_b32_e32 v39, 3, v1
	s_mov_b64 s[44:45], 0
	s_branch .LBB0_391

.LBB0_461:
	v_mbcnt_lo_u32_b32 v0, -1, 0
	v_mbcnt_hi_u32_b32 v0, -1, v0
	s_waitcnt vmcnt(0)
	s_waitcnt lgkmcnt(0)
	v_sub_u32_e32 v0, 0, v0
	v_cmp_eq_u32_e32 vcc, s3, v0
	s_barrier
	s_and_saveexec_b64 s[6:7], vcc
	s_cbranch_execz .LBB0_509
	v_readlane_b32 s16, v255, 29
	s_mul_i32 s16, s16, 3
	s_add_i32 s17, s16, 2
	v_mov_b32_e32 v0, 0x20000
	v_readlane_b32 s21, v255, 6
	s_waitcnt vmcnt(0) lgkmcnt(0)
	ds_read_b32 v2, v0
	s_nop 1
	v_mov_b32_e32 v1, s21
	ds_read_b32 v3, v1
	global_atomic_add v1, v[218:219], v228, off offset:128 sc0
	s_waitcnt vmcnt(0) lgkmcnt(0)
	v_readfirstlane_b32 s21, v1
	v_readfirstlane_b32 s22, v2
	v_readfirstlane_b32 s23, v3
	s_add_i32 s21, s21, 1
	s_mul_i32 s22, s22, s17
	s_cmp_eq_u32 s21, s22
	s_cbranch_scc0 .Lxbb_wait
	buffer_wbl2 sc1
	s_waitcnt vmcnt(0)
	s_add_u32 s36, s10, 0xf003480
	s_addc_u32 s37, s11, 0
	global_atomic_add v1, v161, v228, s[36:37] sc0
	s_waitcnt vmcnt(0)
	v_readfirstlane_b32 s21, v1
	s_add_i32 s21, s21, 1
	s_mul_i32 s23, s23, s17
	s_cmp_eq_u32 s21, s23
	s_cbranch_scc0 .Lxbb_wait
	s_add_u32 s36, s10, 0xf002480
	s_addc_u32 s37, s11, 0
	global_atomic_add v161, v228, s[36:37]
	global_atomic_add v161, v228, s[36:37] offset:256
	global_atomic_add v161, v228, s[36:37] offset:512
	global_atomic_add v161, v228, s[36:37] offset:768
	global_atomic_add v161, v228, s[36:37] offset:1024
	global_atomic_add v161, v228, s[36:37] offset:1280
	global_atomic_add v161, v228, s[36:37] offset:1536
	global_atomic_add v161, v228, s[36:37] offset:1792
	global_atomic_add v161, v228, s[36:37] offset:2048
	global_atomic_add v161, v228, s[36:37] offset:2304
	global_atomic_add v161, v228, s[36:37] offset:2560
	global_atomic_add v161, v228, s[36:37] offset:2816
	global_atomic_add v161, v228, s[36:37] offset:3072
	global_atomic_add v161, v228, s[36:37] offset:3328
	global_atomic_add v161, v228, s[36:37] offset:3584
	global_atomic_add v161, v228, s[36:37] offset:3840

.Lxbb_seen:
	buffer_inv sc1
	s_waitcnt vmcnt(0)
.LBB0_509:
	s_or_b64 exec, exec, s[6:7]
	s_lshl_b64 s[6:7], s[28:29], 22
	v_readlane_b32 s16, v254, 4
	s_add_u32 s19, s16, s6
	v_readlane_b32 s6, v254, 5
	s_addc_u32 s20, s6, s7
	v_readlane_b32 s6, v254, 6
	s_waitcnt lgkmcnt(0)
	s_barrier
	v_mbcnt_lo_u32_b32 v6, -1, 0
	v_mbcnt_hi_u32_b32 v6, -1, v6
	v_readlane_b32 s7, v254, 7
	v_add_u32_e32 v4, s3, v6
	s_andn2_b64 vcc, exec, s[6:7]
	v_readfirstlane_b32 s6, v4
	s_cbranch_vccnz .LBB0_529
	v_lshlrev_b32_e32 v3, 4, v4
	v_add_u32_e32 v1, 0x2000, v3
	v_ashrrev_i32_e32 v0, 31, v1
	v_lshrrev_b32_e32 v0, 22, v0
	v_add_u32_e32 v0, v1, v0
	v_ashrrev_i32_e32 v0, 10, v0
	v_mul_i32_i24_e32 v2, 0x400, v0
	v_sub_u32_e32 v1, v1, v2
	v_lshrrev_b32_e32 v2, 4, v1
	v_bitop3_b32 v2, v2, v1, 32 bitop3:0x6c
	v_ashrrev_i32_e32 v1, 31, v2
	v_lshrrev_b32_e32 v1, 26, v1
	v_add_u32_e32 v5, v2, v1
	v_lshlrev_b32_e32 v7, 3, v0
	v_ashrrev_i32_e32 v1, 6, v5
	v_and_b32_e32 v7, -16, v7
	v_add_u32_e32 v7, v1, v7
	v_and_b32_e32 v8, 3, v1
	s_mov_b32 s17, 0xfffe0
	v_lshrrev_b32_e32 v9, 2, v7
	v_lshlrev_b32_e32 v10, 1, v7
	v_and_b32_e32 v5, 0xc0, v5
	v_and_or_b32 v8, v7, s17, v8
	v_and_b32_e32 v9, 4, v9
	v_and_b32_e32 v10, 24, v10
	v_sub_u32_e32 v2, v2, v5
	v_or3_b32 v8, v8, v9, v10
	v_lshlrev_b32_e32 v9, 5, v0
	v_ashrrev_i16_sdwa v2, v228, sext(v2) dst_sel:DWORD dst_unused:UNUSED_PAD src0_sel:DWORD src1_sel:BYTE_0
	v_and_b32_e32 v9, 32, v9
	v_bfe_i32 v2, v2, 0, 16
	v_add_lshl_u32 v5, v9, v2, 1
	v_lshl_add_u32 v128, v8, 12, v5
	v_lshl_add_u32 v130, v7, 13, v5
	v_bfe_i32 v5, v4, 27, 1
	v_lshrrev_b32_e32 v5, 22, v5
	v_add_u32_e32 v5, v3, v5
	v_and_b32_e32 v5, 0xfffffc00, v5
	v_sub_u32_e32 v3, v3, v5
	v_lshrrev_b32_e32 v5, 4, v3
	v_ashrrev_i32_e32 v8, 31, v4
	v_bitop3_b32 v5, v5, v3, 32 bitop3:0x6c
	v_lshrrev_b32_e32 v8, 26, v8
	v_ashrrev_i32_e32 v3, 31, v5
	v_add_u32_e32 v4, v4, v8
	v_lshrrev_b32_e32 v3, 26, v3
	v_ashrrev_i32_e32 v4, 6, v4
	v_add_u32_e32 v7, v5, v3
	v_lshlrev_b32_e32 v8, 3, v4
	v_ashrrev_i32_e32 v3, 6, v7
	v_and_b32_e32 v8, -16, v8
	v_add_u32_e32 v8, v3, v8
	v_and_b32_e32 v9, 3, v3
	v_lshrrev_b32_e32 v10, 2, v8
	v_lshlrev_b32_e32 v11, 1, v8
	v_and_b32_e32 v7, 0xc0, v7
	s_ashr_i32 s16, s6, 6
	v_and_or_b32 v9, v8, s17, v9
	v_and_b32_e32 v10, 4, v10
	v_and_b32_e32 v11, 24, v11
	v_sub_u32_e32 v5, v5, v7
	s_ashr_i32 s7, s6, 8
	s_lshl_b32 s21, s16, 10
	v_or3_b32 v9, v9, v10, v11
	v_lshlrev_b32_e32 v10, 5, v4
	v_ashrrev_i16_sdwa v5, v228, sext(v5) dst_sel:DWORD dst_unused:UNUSED_PAD src0_sel:DWORD src1_sel:BYTE_0
	v_readlane_b32 s22, v254, 31
	v_and_b32_e32 v10, 32, v10
	v_bfe_i32 v5, v5, 0, 16
	v_readlane_b32 s23, v254, 32
	s_add_u32 s50, s19, s22
	v_add_lshl_u32 v7, v10, v5, 1
	s_addc_u32 s51, s20, s23
	s_add_i32 s22, s21, 0
	v_lshl_add_u32 v160, v9, 12, v7
	s_add_i32 m0, s22, 0x10000
	v_lshl_add_u32 v132, v8, 13, v7
	global_load_lds_dwordx4 v160, s[50:51]
	s_add_i32 m0, s22, 0x12000
	s_add_u32 s24, s50, 0x80000
	global_load_lds_dwordx4 v128, s[50:51]
	s_addc_u32 s25, s51, 0
	s_add_i32 m0, s22, 0x14000
	s_add_i32 s23, s22, 0x2000
	global_load_lds_dwordx4 v160, s[24:25]
	s_add_i32 m0, s22, 0x16000
	v_readlane_b32 s26, v254, 39
	global_load_lds_dwordx4 v128, s[24:25]
	v_readlane_b32 s24, v254, 37
	s_mov_b32 m0, s22
	v_readlane_b32 s25, v254, 38
	v_readlane_b32 s27, v254, 40
	s_nop 3
	global_load_lds_dwordx4 v132, s[24:25]
	s_mov_b32 m0, s23
	s_nop 0
	global_load_lds_dwordx4 v130, s[24:25]
	s_add_i32 s24, s22, 0x4000
	s_mov_b32 m0, s24
	s_add_i32 s25, s22, 0x6000
	global_load_lds_dwordx4 v132, s[26:27]
	s_mov_b32 m0, s25
	s_cmp_eq_u32 s7, 1
	global_load_lds_dwordx4 v130, s[26:27]
	s_cselect_b64 s[38:39], -1, 0
	s_cmp_lg_u32 s7, 1
	s_cbranch_scc1 .LBB0_512
	s_barrier

.LBB0_752:
	s_cmp_eq_u32 s28, 3
	s_cbranch_scc1 .LBB0_148
	v_mbcnt_lo_u32_b32 v0, -1, 0
	v_mbcnt_hi_u32_b32 v0, -1, v0
	s_waitcnt vmcnt(0)
	s_nop 0
	v_sub_u32_e32 v0, 0, v0
	v_cmp_eq_u32_e32 vcc, s3, v0
	s_barrier
	s_and_saveexec_b64 s[6:7], vcc
	s_cbranch_execz .LBB0_147
	v_readlane_b32 s16, v255, 29
	s_mul_i32 s16, s16, 3
	s_add_i32 s17, s16, 3
	v_mov_b32_e32 v0, 0x20000
	v_readlane_b32 s21, v255, 6
	s_waitcnt vmcnt(0) lgkmcnt(0)
	ds_read_b32 v2, v0
	s_nop 1
	v_mov_b32_e32 v1, s21
	ds_read_b32 v3, v1
	global_atomic_add v1, v[218:219], v228, off offset:128 sc0
	s_waitcnt vmcnt(0) lgkmcnt(0)
	v_readfirstlane_b32 s21, v1
	v_readfirstlane_b32 s22, v2
	v_readfirstlane_b32 s23, v3
	s_add_i32 s21, s21, 1
	s_mul_i32 s22, s22, s17
	s_cmp_eq_u32 s21, s22
	s_cbranch_scc0 .Lxbc_wait
	buffer_wbl2 sc1
	s_waitcnt vmcnt(0)
	s_add_u32 s36, s10, 0xf003480
	s_addc_u32 s37, s11, 0
	global_atomic_add v1, v161, v228, s[36:37] sc0
	s_waitcnt vmcnt(0)
	v_readfirstlane_b32 s21, v1
	s_add_i32 s21, s21, 1
	s_mul_i32 s23, s23, s17
	s_cmp_eq_u32 s21, s23
	s_cbranch_scc0 .Lxbc_wait
	s_add_u32 s36, s10, 0xf002480
	s_addc_u32 s37, s11, 0
	global_atomic_add v161, v228, s[36:37]
	global_atomic_add v161, v228, s[36:37] offset:256
	global_atomic_add v161, v228, s[36:37] offset:512
	global_atomic_add v161, v228, s[36:37] offset:768
	global_atomic_add v161, v228, s[36:37] offset:1024
	global_atomic_add v161, v228, s[36:37] offset:1280
	global_atomic_add v161, v228, s[36:37] offset:1536
	global_atomic_add v161, v228, s[36:37] offset:1792
	global_atomic_add v161, v228, s[36:37] offset:2048
	global_atomic_add v161, v228, s[36:37] offset:2304
	global_atomic_add v161, v228, s[36:37] offset:2560
	global_atomic_add v161, v228, s[36:37] offset:2816
	global_atomic_add v161, v228, s[36:37] offset:3072
	global_atomic_add v161, v228, s[36:37] offset:3328
	global_atomic_add v161, v228, s[36:37] offset:3584
	global_atomic_add v161, v228, s[36:37] offset:3840
